# attention KV loop: contiguous score-minus-max subtractions packed (16 packed adds instead of 32 scalar subs per iteration)
# speedup vs baseline: 1.0012x; 1.0012x over previous
.LBB0_567:
	v_cndmask_b32_e64 v158, v136, v158, s[4:5]
	v_pk_add_f32 v[80:81], v[80:81], v[158:159] op_sel_hi:[1,0] neg_lo:[0,1] neg_hi:[0,1]
	v_pk_add_f32 v[82:83], v[82:83], v[158:159] op_sel_hi:[1,0] neg_lo:[0,1] neg_hi:[0,1]
	v_pk_add_f32 v[84:85], v[84:85], v[158:159] op_sel_hi:[1,0] neg_lo:[0,1] neg_hi:[0,1]
	v_pk_add_f32 v[86:87], v[86:87], v[158:159] op_sel_hi:[1,0] neg_lo:[0,1] neg_hi:[0,1]
	v_pk_add_f32 v[88:89], v[88:89], v[158:159] op_sel_hi:[1,0] neg_lo:[0,1] neg_hi:[0,1]
	v_pk_add_f32 v[90:91], v[90:91], v[158:159] op_sel_hi:[1,0] neg_lo:[0,1] neg_hi:[0,1]
	v_pk_add_f32 v[92:93], v[92:93], v[158:159] op_sel_hi:[1,0] neg_lo:[0,1] neg_hi:[0,1]
	v_pk_add_f32 v[94:95], v[94:95], v[158:159] op_sel_hi:[1,0] neg_lo:[0,1] neg_hi:[0,1]
	v_sub_f32_e32 v232, v76, v158
	v_sub_f32_e32 v235, v77, v158
	v_sub_f32_e32 v236, v78, v158
	v_exp_f32_e32 v133, v80
	v_exp_f32_e32 v135, v81
	v_exp_f32_e32 v131, v82
	v_exp_f32_e32 v134, v83
	v_exp_f32_e32 v130, v84
	v_exp_f32_e32 v132, v85
	v_exp_f32_e32 v128, v86
	v_exp_f32_e32 v129, v87
	v_exp_f32_e32 v125, v88
	v_exp_f32_e32 v127, v89
	v_exp_f32_e32 v124, v90
	v_exp_f32_e32 v126, v91
	v_exp_f32_e32 v121, v92
	v_exp_f32_e32 v123, v93
	v_exp_f32_e32 v120, v94
	v_exp_f32_e32 v122, v95
	v_sub_f32_e32 v178, v64, v158
	v_sub_f32_e32 v179, v65, v158
	v_sub_f32_e32 v213, v66, v158
	v_sub_f32_e32 v220, v67, v158
	v_sub_f32_e32 v221, v68, v158
	v_sub_f32_e32 v222, v69, v158
	v_sub_f32_e32 v223, v70, v158
	v_sub_f32_e32 v226, v71, v158
	v_sub_f32_e32 v227, v72, v158
	v_sub_f32_e32 v228, v73, v158
	v_sub_f32_e32 v229, v74, v158
	v_sub_f32_e32 v230, v75, v158
	v_sub_f32_e32 v237, v79, v158
	s_waitcnt lgkmcnt(0)
	s_barrier
	ds_read_b128 v[64:67], v187 offset:32768
	ds_read_b128 v[68:71], v187 offset:45056
	ds_read_b128 v[136:139], v189 offset:32768
	ds_read_b128 v[140:143], v189 offset:45056
	v_exp_f32_e32 v241, v236
	v_exp_f32_e32 v237, v237
	s_waitcnt lgkmcnt(3)
	v_mfma_f32_32x32x16_bf16 v[80:95], v[64:67], v[96:99], 0
	s_waitcnt lgkmcnt(2)
	v_mfma_f32_32x32x16_bf16 v[64:79], v[68:71], v[96:99], 0
	s_waitcnt lgkmcnt(1)
	v_mfma_f32_32x32x16_bf16 v[80:95], v[136:139], v[100:103], v[80:95]
	s_waitcnt lgkmcnt(0)
	v_mfma_f32_32x32x16_bf16 v[64:79], v[140:143], v[100:103], v[64:79]
	ds_read_b128 v[136:139], v190 offset:32768
	ds_read_b128 v[140:143], v190 offset:45056
	s_waitcnt lgkmcnt(1)
	v_mfma_f32_32x32x16_bf16 v[80:95], v[136:139], v[104:107], v[80:95]
	s_waitcnt lgkmcnt(0)
	v_mfma_f32_32x32x16_bf16 v[64:79], v[140:143], v[104:107], v[64:79]
	ds_read_b128 v[136:139], v191 offset:32768
	ds_read_b128 v[140:143], v191 offset:45056
	s_waitcnt lgkmcnt(1)
	v_mfma_f32_32x32x16_bf16 v[80:95], v[136:139], v[108:111], v[80:95]
	s_waitcnt lgkmcnt(0)
	v_mfma_f32_32x32x16_bf16 v[64:79], v[140:143], v[108:111], v[64:79]
	ds_read_b128 v[136:139], v192 offset:32768
	ds_read_b128 v[140:143], v192 offset:45056
	s_waitcnt lgkmcnt(1)
	v_mfma_f32_32x32x16_bf16 v[80:95], v[136:139], v[112:115], v[80:95]
	s_waitcnt lgkmcnt(0)
	v_mfma_f32_32x32x16_bf16 v[64:79], v[140:143], v[112:115], v[64:79]
	ds_read_b128 v[136:139], v193 offset:32768
	ds_read_b128 v[140:143], v193 offset:45056
	s_waitcnt lgkmcnt(1)
	v_mfma_f32_32x32x16_bf16 v[80:95], v[136:139], v[116:119], v[80:95]
	s_waitcnt lgkmcnt(0)
	v_mfma_f32_32x32x16_bf16 v[64:79], v[140:143], v[116:119], v[64:79]
	ds_read_b128 v[136:139], v194 offset:32768
	ds_read_b128 v[140:143], v194 offset:45056
	ds_read_b128 v[144:147], v171
	s_waitcnt lgkmcnt(0)
	v_mfma_f32_32x32x16_bf16 v[80:95], v[136:139], v[144:147], v[80:95]
	v_mfma_f32_32x32x16_bf16 v[64:79], v[140:143], v[144:147], v[64:79]
	ds_read_b128 v[136:139], v195 offset:32768
	ds_read_b128 v[140:143], v195 offset:45056
	ds_read_b128 v[144:147], v171 offset:1024
	s_waitcnt lgkmcnt(0)
	v_mfma_f32_32x32x16_bf16 v[80:95], v[136:139], v[144:147], v[80:95]
	v_mfma_f32_32x32x16_bf16 v[64:79], v[140:143], v[144:147], v[64:79]
	ds_read_b128 v[136:139], v196 offset:32768
	ds_read_b128 v[140:143], v196 offset:45056
	ds_read_b128 v[144:147], v171 offset:2048
	s_waitcnt lgkmcnt(0)
	v_mfma_f32_32x32x16_bf16 v[80:95], v[136:139], v[144:147], v[80:95]
	v_mfma_f32_32x32x16_bf16 v[64:79], v[140:143], v[144:147], v[64:79]
	ds_read_b128 v[136:139], v197 offset:32768
	ds_read_b128 v[140:143], v197 offset:45056
	ds_read_b128 v[144:147], v171 offset:3072
	s_waitcnt lgkmcnt(0)
	v_mfma_f32_32x32x16_bf16 v[80:95], v[136:139], v[144:147], v[80:95]
	v_mfma_f32_32x32x16_bf16 v[64:79], v[140:143], v[144:147], v[64:79]
	ds_read_b128 v[136:139], v199 offset:32768
	ds_read_b128 v[140:143], v199 offset:45056
	ds_read_b128 v[144:147], v171 offset:4096
	s_waitcnt lgkmcnt(0)
	v_mfma_f32_32x32x16_bf16 v[80:95], v[136:139], v[144:147], v[80:95]
	v_mfma_f32_32x32x16_bf16 v[64:79], v[140:143], v[144:147], v[64:79]
	ds_read_b128 v[136:139], v198 offset:32768
	ds_read_b128 v[140:143], v198 offset:45056
	ds_read_b128 v[144:147], v171 offset:5120
	s_waitcnt lgkmcnt(0)
	v_mfma_f32_32x32x16_bf16 v[80:95], v[136:139], v[144:147], v[80:95]
	v_add_f32_e32 v136, 0, v133
	v_add_f32_e32 v136, v135, v136
	v_add_f32_e32 v136, v131, v136
	v_add_f32_e32 v136, v134, v136
	v_add_f32_e32 v136, v130, v136
	v_add_f32_e32 v136, v132, v136
	v_add_f32_e32 v136, v128, v136
	v_add_f32_e32 v136, v129, v136
	v_add_f32_e32 v136, v125, v136
	v_add_f32_e32 v136, v127, v136
	v_add_f32_e32 v136, v124, v136
	v_add_f32_e32 v136, v126, v136
	v_mfma_f32_32x32x16_bf16 v[64:79], v[140:143], v[144:147], v[64:79]
	v_exp_f32_e32 v140, v178
	v_add_f32_e32 v136, v121, v136
	v_exp_f32_e32 v141, v179
	v_add_f32_e32 v136, v123, v136
	v_exp_f32_e32 v142, v213
	v_add_f32_e32 v136, v120, v136
	v_exp_f32_e32 v143, v220
	v_add_f32_e32 v136, v122, v136
	v_exp_f32_e32 v178, v221
	v_add_f32_e32 v136, v140, v136
	v_exp_f32_e32 v179, v222
	v_add_f32_e32 v136, v141, v136
	v_exp_f32_e32 v213, v223
	v_add_f32_e32 v136, v142, v136
	v_exp_f32_e32 v223, v226
	v_add_f32_e32 v136, v143, v136
	v_exp_f32_e32 v226, v227
	v_add_f32_e32 v136, v178, v136
	v_exp_f32_e32 v227, v228
	v_add_f32_e32 v136, v179, v136
	v_exp_f32_e32 v228, v229
	v_add_f32_e32 v136, v213, v136
	v_exp_f32_e32 v229, v230
	v_add_f32_e32 v136, v223, v136
	v_exp_f32_e32 v230, v232
	v_add_f32_e32 v136, v226, v136
	v_exp_f32_e32 v232, v235
	v_add_f32_e32 v136, v227, v136
	v_add_f32_e32 v136, v228, v136
	v_add_f32_e32 v136, v229, v136
	v_add_f32_e32 v136, v230, v136
	v_add_f32_e32 v136, v232, v136
	v_add_f32_e32 v136, v241, v136
	v_add_f32_e32 v235, v237, v136
	v_mov_b32_e32 v236, v235
	v_cvt_pk_bf16_f32 v136, v133, v135
	v_cvt_pk_bf16_f32 v137, v131, v134
	v_cvt_pk_bf16_f32 v138, v130, v132
	s_nop 1
	v_permlane32_swap_b32_e32 v235, v236
	v_cvt_pk_bf16_f32 v139, v128, v129
	v_permlane32_swap_b32_e32 v136, v138
	v_cvt_pk_bf16_f32 v144, v125, v127
	v_cvt_pk_bf16_f32 v145, v124, v126
	v_cvt_pk_bf16_f32 v146, v121, v123
	v_cvt_pk_bf16_f32 v147, v120, v122
	v_cvt_pk_bf16_f32 v220, v140, v141
	v_cvt_pk_bf16_f32 v221, v142, v143
	v_cvt_pk_bf16_f32 v222, v178, v179
	v_cvt_pk_bf16_f32 v223, v213, v223
	v_cvt_pk_bf16_f32 v238, v226, v227
	v_cvt_pk_bf16_f32 v239, v228, v229
	v_cvt_pk_bf16_f32 v240, v230, v232
	v_cvt_pk_bf16_f32 v241, v241, v237
	v_permlane32_swap_b32_e32 v137, v139
	v_permlane32_swap_b32_e32 v144, v146
	v_permlane32_swap_b32_e32 v145, v147
	v_permlane32_swap_b32_e32 v220, v222
	v_permlane32_swap_b32_e32 v221, v223
	v_permlane32_swap_b32_e32 v238, v240
	v_permlane32_swap_b32_e32 v239, v241
	s_add_i32 s4, s15, 64
	s_cmp_lt_u32 s16, 2
	s_cselect_b32 s4, s4, s14
	s_ashr_i32 s5, s4, 31
	s_lshl_b64 s[76:77], s[4:5], 11
	s_mul_hi_i32 s79, s4, s87
	s_mul_i32 s78, s4, s87
	v_lshl_add_u64 v[120:121], v[148:149], 0, s[76:77]
	v_lshl_add_u64 v[124:125], v[156:157], 0, s[76:77]
	v_lshl_add_u64 v[130:131], v[150:151], 0, s[78:79]
	v_lshl_add_u64 v[134:135], v[152:153], 0, s[78:79]
	v_lshl_add_u64 v[140:141], v[154:155], 0, s[78:79]
	global_load_dwordx4 v[120:123], v[120:121], off
	s_nop 0
	global_load_dwordx4 v[124:127], v[124:125], off
	s_nop 0
	global_load_dwordx4 v[128:131], v[130:131], off
	s_nop 0
	global_load_dwordx4 v[132:135], v[134:135], off
	s_nop 0
	global_load_dwordx4 v[140:143], v[140:141], off
	ds_read_b64_tr_b16 v[242:243], v175 offset:0
	ds_read_b64_tr_b16 v[244:245], v175 offset:0x800
	ds_read_b64_tr_b16 v[246:247], v175 offset:0x1000
	ds_read_b64_tr_b16 v[248:249], v175 offset:0x1800
	ds_read_b64_tr_b16 v[250:251], v175 offset:0x2000
	ds_read_b64_tr_b16 v[252:253], v175 offset:0x2800
	ds_read_b64_tr_b16 v[226:227], v175 offset:0x3000
	ds_read_b64_tr_b16 v[228:229], v175 offset:0x3800
	s_waitcnt lgkmcnt(0)
	s_nop 0
	v_mfma_f32_32x32x16_bf16 v[0:15], v[136:139], v[242:245], v[0:15]
	v_mfma_f32_32x32x16_bf16 v[0:15], v[144:147], v[246:249], v[0:15]
	v_mfma_f32_32x32x16_bf16 v[0:15], v[220:223], v[250:253], v[0:15]
	v_mfma_f32_32x32x16_bf16 v[0:15], v[238:241], v[226:229], v[0:15]
	ds_read_b64_tr_b16 v[226:227], v175 offset:0x200
	ds_read_b64_tr_b16 v[228:229], v175 offset:0xa00
	ds_read_b64_tr_b16 v[242:243], v175 offset:0x1200
	ds_read_b64_tr_b16 v[244:245], v175 offset:0x1a00
	ds_read_b64_tr_b16 v[246:247], v175 offset:0x2200
	ds_read_b64_tr_b16 v[248:249], v175 offset:0x2a00
	ds_read_b64_tr_b16 v[250:251], v175 offset:0x3200
	ds_read_b64_tr_b16 v[252:253], v175 offset:0x3a00
	s_waitcnt lgkmcnt(0)
	s_nop 0
	v_mfma_f32_32x32x16_bf16 v[32:47], v[136:139], v[226:229], v[32:47]
	ds_read_b64_tr_b16 v[226:227], v175 offset:0x400
	ds_read_b64_tr_b16 v[228:229], v175 offset:0xc00
	v_mfma_f32_32x32x16_bf16 v[32:47], v[144:147], v[242:245], v[32:47]
	ds_read_b64_tr_b16 v[242:243], v175 offset:0x1400
	ds_read_b64_tr_b16 v[244:245], v175 offset:0x1c00
	v_mfma_f32_32x32x16_bf16 v[32:47], v[220:223], v[246:249], v[32:47]
	ds_read_b64_tr_b16 v[246:247], v175 offset:0x2400
	ds_read_b64_tr_b16 v[248:249], v175 offset:0x2c00
	v_mfma_f32_32x32x16_bf16 v[32:47], v[238:241], v[250:253], v[32:47]
	ds_read_b64_tr_b16 v[250:251], v175 offset:0x3400
	ds_read_b64_tr_b16 v[252:253], v175 offset:0x3c00
	s_waitcnt lgkmcnt(0)
	v_mfma_f32_32x32x16_bf16 v[16:31], v[136:139], v[226:229], v[16:31]
	ds_read_b64_tr_b16 v[226:227], v175 offset:0x600
	ds_read_b64_tr_b16 v[228:229], v175 offset:0xe00
	v_mfma_f32_32x32x16_bf16 v[16:31], v[144:147], v[242:245], v[16:31]
	ds_read_b64_tr_b16 v[242:243], v175 offset:0x1600
	ds_read_b64_tr_b16 v[244:245], v175 offset:0x1e00
	v_mfma_f32_32x32x16_bf16 v[16:31], v[220:223], v[246:249], v[16:31]
	ds_read_b64_tr_b16 v[246:247], v175 offset:0x2600
	ds_read_b64_tr_b16 v[248:249], v175 offset:0x2e00
	v_mfma_f32_32x32x16_bf16 v[16:31], v[238:241], v[250:253], v[16:31]
	ds_read_b64_tr_b16 v[250:251], v175 offset:0x3600
	ds_read_b64_tr_b16 v[252:253], v175 offset:0x3e00
	s_waitcnt lgkmcnt(0)
	v_mfma_f32_32x32x16_bf16 v[48:63], v[136:139], v[226:229], v[48:63]
	v_max_f32_e32 v136, v81, v81
	v_max_f32_e32 v137, v80, v80
	v_max_f32_e32 v136, v137, v136
	v_max3_f32 v136, v136, v82, v83
	v_max3_f32 v136, v136, v84, v85
	v_max3_f32 v136, v136, v86, v87
	v_max3_f32 v136, v136, v88, v89
	v_max3_f32 v136, v136, v90, v91
	v_mfma_f32_32x32x16_bf16 v[48:63], v[144:147], v[242:245], v[48:63]
	v_max3_f32 v136, v136, v92, v93
	v_max3_f32 v136, v136, v94, v95
	v_max3_f32 v136, v136, v64, v65
	v_max3_f32 v136, v136, v66, v67
	v_max3_f32 v136, v136, v68, v69
	v_max3_f32 v136, v136, v70, v71
	v_max3_f32 v136, v136, v72, v73
	v_max3_f32 v136, v136, v74, v75
	v_mfma_f32_32x32x16_bf16 v[48:63], v[220:223], v[246:249], v[48:63]
	v_max3_f32 v136, v136, v76, v77
	v_max3_f32 v136, v136, v78, v79
	v_mov_b32_e32 v137, v136
	s_nop 1
	v_permlane32_swap_b32_e32 v136, v137
	v_max_f32_e32 v137, v137, v137
	v_max_f32_e32 v136, v136, v136
	v_max_f32_e32 v136, v136, v137
	v_sub_f32_e32 v137, v136, v158
	v_cmp_ge_f32_e32 vcc, s90, v137
	v_max_f32_e32 v137, v158, v158
	v_mfma_f32_32x32x16_bf16 v[48:63], v[238:241], v[250:253], v[48:63]
	v_max_f32_e32 v136, v137, v136
	v_sub_f32_e32 v137, v158, v136
	v_exp_f32_e32 v137, v137
	s_cmp_eq_u64 vcc, exec
	s_cselect_b64 s[4:5], -1, 0
	s_barrier
	s_waitcnt vmcnt(0)
	v_cndmask_b32_e64 v232, v137, 1.0, s[4:5]
	v_cmp_gt_f32_e32 vcc, 1.0, v232
	s_waitcnt vmcnt(4)
	ds_write_b128 v182, v[120:123] offset:16384
	s_waitcnt vmcnt(3)
	ds_write_b128 v183, v[124:127] offset:16384
	s_waitcnt vmcnt(2)
	ds_write_b128 v184, v[128:131] offset:57344
	s_waitcnt vmcnt(1)
	ds_write_b128 v185, v[132:135] offset:57344
	s_waitcnt vmcnt(0)
	ds_write_b128 v186, v[140:143] offset:57344
	s_cbranch_vccz .LBB0_571
	s_and_saveexec_b64 s[6:7], s[2:3]
	ds_write_b32 v173, v232 offset:128
	s_or_b64 exec, exec, s[6:7]
	s_waitcnt lgkmcnt(0)
	v_add_u32_e32 v132, v169, v176
	ds_read_b128 v[120:123], v132 offset:224
	ds_read_b128 v[124:127], v132 offset:192
	ds_read_b128 v[128:131], v132 offset:160
	ds_read_b128 v[132:135], v132 offset:128
	s_waitcnt lgkmcnt(3)
	v_pk_mul_f32 v[12:13], v[12:13], v[120:121]
	s_waitcnt lgkmcnt(2)
	v_pk_mul_f32 v[8:9], v[8:9], v[124:125]
	s_waitcnt lgkmcnt(1)
	v_pk_mul_f32 v[4:5], v[4:5], v[128:129]
	v_pk_mul_f32 v[14:15], v[14:15], v[122:123]
	v_pk_mul_f32 v[10:11], v[10:11], v[126:127]
	v_pk_mul_f32 v[6:7], v[6:7], v[130:131]
	s_waitcnt lgkmcnt(0)
	v_pk_mul_f32 v[2:3], v[2:3], v[134:135]
	v_pk_mul_f32 v[0:1], v[0:1], v[132:133]
	v_pk_mul_f32 v[44:45], v[44:45], v[120:121]
	v_pk_mul_f32 v[40:41], v[40:41], v[124:125]
	v_pk_mul_f32 v[36:37], v[36:37], v[128:129]
	v_pk_mul_f32 v[46:47], v[46:47], v[122:123]
	v_pk_mul_f32 v[42:43], v[42:43], v[126:127]
	v_pk_mul_f32 v[38:39], v[38:39], v[130:131]
	v_pk_mul_f32 v[34:35], v[34:35], v[134:135]
	v_pk_mul_f32 v[32:33], v[32:33], v[132:133]
	v_pk_mul_f32 v[28:29], v[28:29], v[120:121]
	v_pk_mul_f32 v[24:25], v[24:25], v[124:125]
	v_pk_mul_f32 v[20:21], v[20:21], v[128:129]
	v_pk_mul_f32 v[30:31], v[30:31], v[122:123]
	v_pk_mul_f32 v[26:27], v[26:27], v[126:127]
	v_pk_mul_f32 v[22:23], v[22:23], v[130:131]
	v_pk_mul_f32 v[18:19], v[18:19], v[134:135]
	v_pk_mul_f32 v[16:17], v[16:17], v[132:133]
	v_pk_mul_f32 v[60:61], v[60:61], v[120:121]
	v_pk_mul_f32 v[56:57], v[56:57], v[124:125]
	v_pk_mul_f32 v[52:53], v[52:53], v[128:129]
	v_pk_mul_f32 v[62:63], v[62:63], v[122:123]
	v_pk_mul_f32 v[58:59], v[58:59], v[126:127]
	v_pk_mul_f32 v[54:55], v[54:55], v[130:131]
	v_pk_mul_f32 v[50:51], v[50:51], v[134:135]
	v_pk_mul_f32 v[48:49], v[48:49], v[132:133]
.LBB0_571:
	v_cndmask_b32_e64 v158, v136, v158, s[4:5]
	v_pk_add_f32 v[80:81], v[80:81], v[158:159] op_sel_hi:[1,0] neg_lo:[0,1] neg_hi:[0,1]
	v_pk_add_f32 v[82:83], v[82:83], v[158:159] op_sel_hi:[1,0] neg_lo:[0,1] neg_hi:[0,1]
	v_pk_add_f32 v[84:85], v[84:85], v[158:159] op_sel_hi:[1,0] neg_lo:[0,1] neg_hi:[0,1]
	v_pk_add_f32 v[86:87], v[86:87], v[158:159] op_sel_hi:[1,0] neg_lo:[0,1] neg_hi:[0,1]
	v_pk_add_f32 v[88:89], v[88:89], v[158:159] op_sel_hi:[1,0] neg_lo:[0,1] neg_hi:[0,1]
	v_pk_add_f32 v[90:91], v[90:91], v[158:159] op_sel_hi:[1,0] neg_lo:[0,1] neg_hi:[0,1]
	v_pk_add_f32 v[92:93], v[92:93], v[158:159] op_sel_hi:[1,0] neg_lo:[0,1] neg_hi:[0,1]
	v_pk_add_f32 v[94:95], v[94:95], v[158:159] op_sel_hi:[1,0] neg_lo:[0,1] neg_hi:[0,1]
	v_exp_f32_e32 v136, v80
	v_exp_f32_e32 v230, v81
	v_exp_f32_e32 v137, v82
	v_exp_f32_e32 v229, v83
	v_exp_f32_e32 v138, v84
	v_exp_f32_e32 v228, v85
	v_exp_f32_e32 v139, v86
	v_exp_f32_e32 v213, v87
	v_exp_f32_e32 v144, v88
	v_exp_f32_e32 v147, v89
	v_exp_f32_e32 v145, v90
	v_exp_f32_e32 v146, v91
	v_exp_f32_e32 v141, v92
	v_exp_f32_e32 v143, v93
	v_exp_f32_e32 v140, v94
	v_exp_f32_e32 v142, v95
	v_add_f32_e32 v80, v231, v233
	v_fmac_f32_e32 v80, v200, v188
	v_add_f32_e32 v188, v235, v236
	s_addk_i32 s15, 0x80
	s_add_i32 s13, s13, 2
	s_addk_i32 s14, 0x80
	v_fmac_f32_e32 v188, v80, v234
	v_pk_add_f32 v[132:133], v[64:65], v[158:159] op_sel_hi:[1,0] neg_lo:[0,1] neg_hi:[0,1]
	v_pk_add_f32 v[134:135], v[66:67], v[158:159] op_sel_hi:[1,0] neg_lo:[0,1] neg_hi:[0,1]
	v_pk_add_f32 v[124:125], v[68:69], v[158:159] op_sel_hi:[1,0] neg_lo:[0,1] neg_hi:[0,1]
	v_pk_add_f32 v[126:127], v[70:71], v[158:159] op_sel_hi:[1,0] neg_lo:[0,1] neg_hi:[0,1]
	v_pk_add_f32 v[128:129], v[72:73], v[158:159] op_sel_hi:[1,0] neg_lo:[0,1] neg_hi:[0,1]
	v_pk_add_f32 v[130:131], v[74:75], v[158:159] op_sel_hi:[1,0] neg_lo:[0,1] neg_hi:[0,1]
	v_pk_add_f32 v[120:121], v[76:77], v[158:159] op_sel_hi:[1,0] neg_lo:[0,1] neg_hi:[0,1]
	v_pk_add_f32 v[122:123], v[78:79], v[158:159] op_sel_hi:[1,0] neg_lo:[0,1] neg_hi:[0,1]
	s_cmp_ge_u32 s13, s12
	s_waitcnt lgkmcnt(0)
	s_barrier
	s_cbranch_scc1 .LBB0_573
	v_mov_b32_e32 v200, v232
	s_branch .LBB0_563
